# SSD prompt chunk loop: one static s_setprio 1 for waves 4-7 (younger half) for the duration of the loop
# baseline (speedup 1.0000x reference)
.LBB0_184:
	v_writelane_b32 v254, s52, 62
	s_mov_b32 s0, s54
	v_writelane_b32 v255, s0, 2
	v_writelane_b32 v254, s53, 63
	v_writelane_b32 v254, s50, 17
	v_writelane_b32 v255, s1, 3
	s_cmpk_gt_i32 s54, 0xff
	v_writelane_b32 v254, s51, 18
	s_cbranch_scc1 .LBB0_217
	v_readlane_b32 s0, v254, 56
	v_readlane_b32 s1, v254, 57
	s_load_dwordx4 s[4:7], s[0:1], 0x70
	v_lshlrev_b32_e32 v4, 4, v174
	s_load_dwordx2 s[0:1], s[0:1], 0x108
	v_and_b32_e32 v4, 0xf0, v4
	v_mov_b32_e32 v5, v26
	s_waitcnt lgkmcnt(0)
	v_writelane_b32 v255, s4, 16
	v_and_b32_e32 v2, 15, v174
	s_add_u32 s2, s0, 0x10788000
	v_writelane_b32 v255, s5, 17
	v_writelane_b32 v255, s6, 18
	s_addc_u32 s3, s1, 0
	v_writelane_b32 v255, s7, 19
	s_add_u32 s4, s0, 0x5100000
	s_addc_u32 s5, s1, 0
	v_writelane_b32 v255, s4, 20
	s_add_u32 s0, s0, 0x15a08000
	v_lshlrev_b32_e32 v6, 3, v174
	v_writelane_b32 v255, s5, 21
	v_writelane_b32 v255, s2, 22
	s_waitcnt vmcnt(0)
	v_lshlrev_b32_e32 v92, 4, v177
	v_readlane_b32 s6, v254, 14
	v_writelane_b32 v255, s3, 23
	v_lshl_add_u64 v[90:91], s[2:3], 0, v[4:5]
	v_and_b32_e32 v5, 63, v174
	v_writelane_b32 v255, s0, 24
	s_addc_u32 s0, s1, 0
	v_lshlrev_b32_e32 v12, 3, v5
	v_readlane_b32 s3, v254, 13
	v_ashrrev_i32_e32 v112, 2, v174
	v_writelane_b32 v255, s0, 25
	v_and_b32_e32 v6, 24, v6
	v_or_b32_e32 v114, v92, v2
	s_movk_i32 s0, 0x50
	v_add_u32_e32 v115, s3, v12
	v_add_u32_e32 v116, s6, v12
	v_and_b32_e32 v12, -4, v174
	v_mul_lo_u32 v9, v114, s0
	v_lshlrev_b32_e32 v8, 1, v6
	v_add_u32_e32 v117, s6, v12
	v_add_u32_e32 v118, s3, v12
	v_mul_lo_u32 v12, v112, s0
	v_readlane_b32 s0, v254, 11
	v_readlane_b32 s2, v254, 12
	s_movk_i32 s7, 0x110
	v_ashrrev_i32_e32 v1, 4, v174
	v_bfe_u32 v7, v174, 4, 2
	v_add3_u32 v119, s0, v8, v12
	v_add3_u32 v120, s2, v8, v12
	v_mul_lo_u32 v8, v114, s7
	v_lshlrev_b32_e32 v113, 1, v5
	v_add_u32_e32 v12, 0, v8
	v_lshlrev_b32_e32 v8, 2, v7
	v_cmp_eq_u32_e64 s[24:25], 0, v5
	v_cmp_gt_u32_e64 s[96:97], 2, v5
	v_cmp_gt_u32_e64 s[30:31], 4, v5
	v_cmp_gt_u32_e64 s[34:35], 8, v5
	v_cmp_gt_u32_e64 s[36:37], 16, v5
	v_cmp_gt_u32_e64 s[38:39], 32, v5
	v_mul_lo_u32 v5, v1, s7
	v_add3_u32 v124, 0, v4, v5
	v_or_b32_e32 v4, 2, v8
	v_cmp_gt_i32_e64 s[46:47], v4, v114
	v_or_b32_e32 v4, 3, v8
	v_cmp_gt_i32_e64 s[48:49], v4, v114
	v_or_b32_e32 v4, 16, v8
	v_lshl_add_u32 v126, v4, 2, s3
	v_cmp_gt_i32_e64 s[52:53], v4, v114
	v_or_b32_e32 v4, 17, v8
	v_cmp_gt_i32_e64 s[54:55], v4, v114
	v_or_b32_e32 v4, 18, v8
	v_cmp_gt_i32_e64 s[56:57], v4, v114
	v_or_b32_e32 v4, 19, v8
	v_cmp_gt_i32_e64 s[58:59], v4, v114
	v_or_b32_e32 v4, 32, v8
	v_lshl_add_u32 v127, v4, 2, s3
	v_cmp_gt_i32_e64 s[62:63], v4, v114
	v_or_b32_e32 v4, 33, v8
	v_cmp_gt_i32_e64 s[64:65], v4, v114
	v_or_b32_e32 v4, 34, v8
	v_cmp_gt_i32_e64 s[66:67], v4, v114
	v_or_b32_e32 v4, 35, v8
	v_cmp_gt_i32_e64 s[68:69], v4, v114
	v_or_b32_e32 v4, 48, v8
	v_lshl_add_u32 v128, v4, 2, s3
	v_cmp_gt_i32_e64 s[72:73], v4, v114
	v_or_b32_e32 v4, 49, v8
	v_cmp_gt_i32_e64 s[74:75], v4, v114
	v_or_b32_e32 v4, 50, v8
	v_cmp_gt_i32_e64 s[76:77], v4, v114
	v_or_b32_e32 v4, 51, v8
	v_cmp_gt_i32_e64 s[78:79], v4, v114
	v_or_b32_e32 v4, 64, v8
	v_lshl_add_u32 v129, v4, 2, s3
	v_cmp_gt_i32_e64 s[82:83], v4, v114
	v_or_b32_e32 v4, 0x41, v8
	v_cmp_gt_i32_e64 s[84:85], v4, v114
	v_or_b32_e32 v4, 0x42, v8
	v_cmp_gt_i32_e64 s[86:87], v4, v114
	v_or_b32_e32 v4, 0x43, v8
	v_cmp_gt_i32_e64 s[88:89], v4, v114
	v_or_b32_e32 v4, 0x50, v8
	v_lshl_add_u32 v130, v4, 2, s3
	v_cmp_gt_i32_e64 s[92:93], v4, v114
	v_or_b32_e32 v4, 0x51, v8
	v_cmp_gt_i32_e64 s[94:95], v4, v114
	v_or_b32_e32 v4, 0x52, v8
	v_readlane_b32 s1, v254, 10
	v_lshlrev_b32_e32 v11, 3, v7
	v_cmp_gt_i32_e64 s[70:71], v4, v114
	v_or_b32_e32 v4, 0x53, v8
	v_add_u32_e32 v10, s1, v9
	v_lshlrev_b32_e32 v14, 2, v114
	v_add_u32_e32 v17, s0, v6
	v_add_u32_e32 v18, s1, v6
	v_add3_u32 v123, s0, v9, v11
	v_cmp_lt_i32_e64 s[0:1], 4, v177
	v_cmp_gt_i32_e64 s[80:81], v4, v114
	v_or_b32_e32 v4, 0x60, v8
	v_add_u32_e32 v122, s6, v14
	v_writelane_b32 v255, s0, 26
	v_lshl_add_u32 v131, v4, 2, s3
	v_cmp_gt_i32_e64 s[6:7], v4, v114
	v_or_b32_e32 v4, 0x61, v8
	v_writelane_b32 v255, s1, 27
	v_cmp_gt_i32_e64 s[0:1], v4, v114
	v_or_b32_e32 v4, 0x62, v8
	v_cmp_gt_i32_e64 s[8:9], v4, v114
	v_or_b32_e32 v4, 0x63, v8
	v_cmp_lt_i32_e64 s[12:13], 6, v177
	v_and_b32_e32 v13, 48, v174
	v_cmp_gt_i32_e64 s[10:11], v4, v114
	v_writelane_b32 v255, s12, 28
	v_or_b32_e32 v4, 0x70, v8
	v_add_u32_e32 v121, s3, v14
	v_add_u32_e32 v14, s2, v6
	v_add_u32_e32 v125, s3, v13
	v_writelane_b32 v255, s13, 29
	v_lshl_add_u32 v132, v4, 2, s3
	v_cmp_gt_i32_e64 s[2:3], v4, v114
	v_or_b32_e32 v4, 0x71, v8
	v_ashrrev_i32_e32 v16, 7, v174
	v_writelane_b32 v255, s2, 30
	v_bfe_u32 v3, v174, 2, 2
	v_lshlrev_b32_e32 v9, 5, v177
	v_writelane_b32 v255, s3, 31
	v_cmp_gt_i32_e64 s[2:3], v4, v114
	v_or_b32_e32 v4, 0x72, v8
	v_add_u32_e32 v15, 0, v13
	v_writelane_b32 v255, s2, 32
	v_add3_u32 v9, 0, v9, v6
	v_mul_u32_u24_e32 v5, 0x110, v2
	v_writelane_b32 v255, s3, 33
	v_cmp_gt_i32_e64 s[2:3], v4, v114
	v_or_b32_e32 v4, 0x73, v8
	v_cmp_gt_u32_e64 s[4:5], 64, v174
	v_writelane_b32 v255, s2, 34
	v_cmp_lt_i32_e64 s[18:19], -1, v177
	v_cmp_gt_i32_e64 s[42:43], v8, v114
	v_writelane_b32 v255, s3, 35
	v_cmp_gt_i32_e64 s[2:3], v4, v114
	v_or_b32_e32 v4, v8, v3
	v_or_b32_e32 v3, v11, v3
	v_writelane_b32 v255, s2, 36
	v_mul_u32_u24_e32 v19, 0x50, v4
	v_lshlrev_b32_e32 v4, 9, v7
	v_writelane_b32 v255, s3, 37
	v_cmp_lt_i32_e64 s[2:3], -1, v16
	v_cmp_lt_i32_e64 s[44:45], v8, v114
	v_cmp_lt_i32_e64 s[28:29], 0, v177
	v_writelane_b32 v255, s2, 38
	v_cmp_lt_i32_e64 s[40:41], 1, v177
	v_cmp_lt_i32_e64 s[50:51], 2, v177
	v_writelane_b32 v255, s3, 39
	v_cmp_lt_i32_e64 s[2:3], 0, v16
	v_cmp_lt_i32_e64 s[60:61], 3, v177
	v_cmp_lt_i32_e64 s[90:91], 5, v177
	v_writelane_b32 v255, s2, 40
	v_ashrrev_i32_e32 v93, 31, v92
	v_add_u32_e32 v133, 0x80, v112
	v_writelane_b32 v255, s3, 41
	v_cmp_lt_i32_e64 s[2:3], 1, v16
	v_lshlrev_b32_e32 v94, 1, v6
	v_lshlrev_b32_e32 v96, 1, v8
	v_writelane_b32 v255, s2, 42
	v_add_u32_e32 v134, v10, v11
	v_add_u32_e32 v135, v12, v13
	v_writelane_b32 v255, s3, 43
	v_cmp_lt_i32_e64 s[2:3], 2, v16
	v_mul_u32_u24_e32 v16, 0x50, v3
	v_mul_u32_u24_e32 v3, 0x110, v3
	v_writelane_b32 v255, s2, 44
	v_add_u32_e32 v136, v18, v16
	v_add_u32_e32 v137, v9, v3
	v_writelane_b32 v255, s3, 45
	v_add_u32_e32 v138, v14, v16
	v_readlane_b32 s12, v255, 2
	v_readlane_b32 s13, v255, 3
	v_writelane_b32 v255, s10, 46
	v_lshlrev_b32_e32 v98, 2, v2
	v_lshlrev_b32_e32 v100, 2, v4
	v_add_u32_e32 v139, v15, v5
	v_add_u32_e32 v140, v17, v19
	s_mov_b32 s2, s12
	v_writelane_b32 v255, s11, 47
	v_readfirstlane_b32 s32, v174
	s_lshr_b32 s32, s32, 8
	s_cmp_eq_u32 s32, 0
	s_mov_b32 s32, 0
	s_cbranch_scc1 .Lssd_noprio
	s_setprio 1
.Lssd_noprio:
	s_branch .LBB0_187
.LBB0_186:
	v_readlane_b32 s12, v254, 56
	v_readlane_b32 s13, v254, 57
	s_load_dwordx2 s[12:13], s[12:13], 0x100
	v_readlane_b32 s2, v255, 48
	s_lshl_b32 s14, s2, 4
	v_readlane_b32 s2, v255, 49
	s_or_b32 s14, s14, s2
	s_ashr_i32 s15, s14, 31
	s_lshl_b64 s[14:15], s[14:15], 15
	s_waitcnt lgkmcnt(0)
	s_add_u32 s12, s12, s14
	v_readlane_b32 s2, v255, 51
	s_addc_u32 s13, s13, s15
	s_lshl_b32 s14, s2, 9
	s_add_u32 s12, s12, s14
	s_addc_u32 s13, s13, 0
	s_waitcnt vmcnt(12)
	v_lshl_add_u64 v[2:3], v[92:93], 2, s[12:13]
	v_mov_b32_e32 v99, v26
	v_lshl_add_u64 v[2:3], v[2:3], 0, v[98:99]
	v_mov_b32_e32 v101, v26
	v_lshl_add_u64 v[2:3], v[2:3], 0, v[100:101]
	s_mov_b64 s[12:13], 0x4200000
	v_lshl_add_u64 v[4:5], v[2:3], 0, s[12:13]
	s_mov_b32 s12, 0x4200000
	s_waitcnt vmcnt(11)
	v_add_co_u32_e32 v6, vcc, s12, v2
	v_readlane_b32 s12, v254, 62
	s_nop 0
	v_addc_co_u32_e32 v7, vcc, 0, v3, vcc
	v_readlane_b32 s2, v255, 50
	v_add_co_u32_e32 v2, vcc, 0x4202000, v2
	s_add_i32 s2, s2, s12
	s_nop 0
	v_addc_co_u32_e32 v3, vcc, 0, v3, vcc
	s_cmpk_gt_i32 s2, 0xff
	global_store_dword v[6:7], v42, off
	global_store_dword v[4:5], v43, off offset:512
	global_store_dword v[4:5], v44, off offset:1024
	global_store_dword v[4:5], v45, off offset:1536
	global_store_dword v[2:3], v46, off
	global_store_dword v[2:3], v47, off offset:512
	global_store_dword v[2:3], v48, off offset:1024
	v_readlane_b32 s13, v254, 63
	global_store_dword v[2:3], v49, off offset:1536
	s_cbranch_scc1 .LBB0_217

.LBB0_217:
	s_setprio 0
	v_readlane_b32 s0, v255, 14
	v_readlane_b32 s68, v255, 10
	v_readlane_b32 s1, v255, 15
	v_readlane_b32 s69, v255, 11
	v_readlane_b32 s58, v254, 20
	v_readlane_b32 s60, v254, 22
	v_readlane_b32 s62, v254, 24
	v_readlane_b32 s64, v254, 26
	v_readlane_b32 s66, v254, 28
	v_readlane_b32 s72, v254, 30
	v_readlane_b32 s74, v254, 32
	v_readlane_b32 s76, v254, 34
	v_readlane_b32 s78, v254, 36
	v_readlane_b32 s86, v254, 38
	v_readlane_b32 s88, v254, 40
	v_readlane_b32 s90, v254, 42
	v_readlane_b32 s92, v254, 44
	v_readlane_b32 s94, v254, 46
	v_readlane_b32 s96, v254, 48
	v_readlane_b32 s50, v254, 50
	v_readlane_b32 s52, v254, 52
	v_readlane_b32 s80, v254, 54
	s_andn2_b64 vcc, exec, s[0:1]
	v_readlane_b32 s54, v254, 19
	v_readlane_b32 s70, v255, 12
	v_readlane_b32 s71, v255, 13
	v_readlane_b32 s59, v254, 21
	v_readlane_b32 s61, v254, 23
	v_readlane_b32 s63, v254, 25
	v_readlane_b32 s65, v254, 27
	v_readlane_b32 s67, v254, 29
	v_readlane_b32 s73, v254, 31
	v_readlane_b32 s75, v254, 33
	v_readlane_b32 s77, v254, 35
	v_readlane_b32 s79, v254, 37
	v_readlane_b32 s87, v254, 39
	v_readlane_b32 s89, v254, 41
	v_readlane_b32 s91, v254, 43
	v_readlane_b32 s93, v254, 45
	v_readlane_b32 s95, v254, 47
	v_readlane_b32 s97, v254, 49
	v_readlane_b32 s51, v254, 51
	v_readlane_b32 s53, v254, 53
	v_readlane_b32 s81, v254, 55
	s_movk_i32 s55, 0x4200
	s_movk_i32 s49, 0x41ff
	s_movk_i32 s68, 0x7f0
	s_movk_i32 s69, 0x5000
	s_mov_b32 s82, 0xb000
	s_mov_b32 s83, 0xd000
	s_movk_i32 s84, 0x5800
	s_movk_i32 s85, 0x7fd
	s_mov_b64 s[56:57], 0xb000
	s_cbranch_vccnz .LBB0_248
	s_mov_b32 s48, 1
	s_branch .Lss_entry
